# speedup vs baseline: 1.0261x; 1.0005x over previous
; __device__ __forceinline__ int tid_() { int t = threadIdx.x; asm volatile("" : "+v"(t)); return t; }
; __device__ __forceinline__ void phase_final(float* x, const float* g, int bid, int nb) {
;   const int tidn = tid_();
;   int wid = tidn >> 6, lane = tidn & 63;
;   for (int r = bid * 8 + wid; r < T_ALL; r += nb * 8) {
;     float* xr = x + (long)r * D;
;     float4 v[4];
;     float ss = 0.f;
; #pragma unroll
;     for (int i = 0; i < 4; ++i) {
;       v[i] = *(const float4*)(xr + i * 256 + lane * 4);
;       ss += v[i].x * v[i].x + v[i].y * v[i].y + v[i].z * v[i].z + v[i].w * v[i].w;
;     }
; #pragma unroll
;     for (int o = 32; o >= 1; o >>= 1) ss += shfl_xor_l(ss, lane, o);
;     float rinv = rsqrtf(ss * (1.0f / D) + EPS);
; #pragma unroll
;     for (int i = 0; i < 4; ++i) {
;       float4 gg = *(const float4*)(g + i * 256 + lane * 4);
;       float4 o = make_float4(v[i].x * rinv * gg.x, v[i].y * rinv * gg.y, v[i].z * rinv * gg.z, v[i].w * rinv * gg.w);
;       *(float4*)(xr + i * 256 + lane * 4) = o;
;     }
;   }
; }
.LBB0_13:
	global_load_dwordx4 v[12:15], v[4:5], off
	global_load_dwordx4 v[16:19], v[2:3], off
	global_load_dwordx4 v[20:23], v[4:5], off offset:1024
	global_load_dwordx4 v[208:211], v[4:5], off offset:2048
	global_load_dwordx4 v[212:215], v[4:5], off offset:3072
	global_load_dwordx4 v[196:199], v[2:3], off offset:1024
	global_load_dwordx4 v[200:203], v[2:3], off offset:2048
	global_load_dwordx4 v[204:207], v[2:3], off offset:3072
	v_add_u32_e32 v6, s62, v6
	s_mov_b32 s10, 0x13fff
	s_waitcnt vmcnt(0)
	v_mov_b32_e32 v26, v13
	v_mov_b32_e32 v24, v12
	s_waitcnt vmcnt(0)
	v_mov_b32_e32 v27, v21
	v_mov_b32_e32 v25, v20
	v_pk_mul_f32 v[26:27], v[26:27], v[26:27]
	v_mov_b32_e32 v28, v15
	v_pk_fma_f32 v[24:25], v[24:25], v[24:25], v[26:27]
	v_mov_b32_e32 v26, v14
	v_mov_b32_e32 v27, v22
	v_mov_b32_e32 v29, v23
	v_pk_fma_f32 v[24:25], v[26:27], v[26:27], v[24:25]
	s_nop 0
	v_pk_fma_f32 v[32:33], v[28:29], v[28:29], v[24:25]
	v_mov_b64_e32 v[24:25], v[208:209]
	v_mov_b64_e32 v[26:27], v[210:211]
	v_mov_b64_e32 v[28:29], v[212:213]
	v_mov_b64_e32 v[30:31], v[214:215]
	v_add_f32_e32 v32, v32, v33
	s_waitcnt vmcnt(1)
	v_mov_b32_e32 v36, v25
	s_waitcnt vmcnt(0)
	v_mov_b32_e32 v37, v29
	v_mov_b32_e32 v34, v24
	v_mov_b32_e32 v35, v28
	v_pk_mul_f32 v[36:37], v[36:37], v[36:37]
	v_mov_b32_e32 v38, v27
	v_pk_fma_f32 v[34:35], v[34:35], v[34:35], v[36:37]
	v_mov_b32_e32 v36, v26
	v_mov_b32_e32 v37, v30
	v_mov_b32_e32 v39, v31
	v_pk_fma_f32 v[34:35], v[36:37], v[36:37], v[34:35]
	s_nop 0
	v_pk_fma_f32 v[34:35], v[38:39], v[38:39], v[34:35]
	s_nop 0
	v_add_f32_e32 v32, v32, v34
	v_add_f32_e32 v32, v32, v35
	ds_bpermute_b32 v33, v0, v32
	s_waitcnt lgkmcnt(0)
	v_add_f32_e32 v32, v32, v33
	ds_bpermute_b32 v33, v7, v32
	s_waitcnt lgkmcnt(0)
	v_add_f32_e32 v32, v32, v33
	ds_bpermute_b32 v33, v8, v32
	s_waitcnt lgkmcnt(0)
	v_add_f32_e32 v32, v32, v33
	ds_bpermute_b32 v33, v9, v32
	s_waitcnt lgkmcnt(0)
	v_add_f32_e32 v32, v32, v33
	ds_bpermute_b32 v33, v10, v32
	s_waitcnt lgkmcnt(0)
	v_add_f32_e32 v32, v32, v33
	ds_bpermute_b32 v33, v11, v32
	s_waitcnt lgkmcnt(0)
	v_add_f32_e32 v32, v32, v33
	v_fmamk_f32 v32, v32, 0x3a800000, v183
	v_cmp_gt_f32_e32 vcc, s18, v32
	v_mul_f32_e32 v33, 0x4b800000, v32
	s_nop 0
	v_cndmask_b32_e32 v32, v32, v33, vcc
	v_rsq_f32_e32 v32, v32
	s_nop 0
	v_mul_f32_e32 v33, 0x45800000, v32
	v_cndmask_b32_e32 v32, v32, v33, vcc
	v_pk_mul_f32 v[12:13], v[12:13], v[32:33] op_sel_hi:[1,0]
	v_pk_mul_f32 v[14:15], v[14:15], v[32:33] op_sel_hi:[1,0]
	v_pk_mul_f32 v[12:13], v[16:17], v[12:13]
	v_pk_mul_f32 v[14:15], v[18:19], v[14:15]
	global_store_dwordx4 v[4:5], v[12:15], off
	s_nop 1
	v_mov_b64_e32 v[12:13], v[196:197]
	v_mov_b64_e32 v[14:15], v[198:199]
	v_pk_mul_f32 v[16:17], v[20:21], v[32:33] op_sel_hi:[1,0]
	v_cmp_lt_i32_e32 vcc, s10, v6
	s_or_b64 s[8:9], vcc, s[8:9]
	s_nop 0
	v_pk_mul_f32 v[12:13], v[12:13], v[16:17]
	v_pk_mul_f32 v[16:17], v[22:23], v[32:33] op_sel_hi:[1,0]
	s_nop 0
	v_pk_mul_f32 v[14:15], v[14:15], v[16:17]
	global_store_dwordx4 v[4:5], v[12:15], off offset:1024
	s_nop 1
	v_mov_b64_e32 v[12:13], v[200:201]
	v_mov_b64_e32 v[14:15], v[202:203]
	v_pk_mul_f32 v[16:17], v[24:25], v[32:33] op_sel_hi:[1,0]
	s_nop 0
	v_pk_mul_f32 v[12:13], v[16:17], v[12:13]
	v_pk_mul_f32 v[16:17], v[26:27], v[32:33] op_sel_hi:[1,0]
	s_nop 0
	v_pk_mul_f32 v[14:15], v[16:17], v[14:15]
	global_store_dwordx4 v[4:5], v[12:15], off offset:2048
	s_nop 1
	v_mov_b64_e32 v[12:13], v[204:205]
	v_mov_b64_e32 v[14:15], v[206:207]
	v_pk_mul_f32 v[16:17], v[28:29], v[32:33] op_sel_hi:[1,0]
	s_nop 0
	v_pk_mul_f32 v[12:13], v[16:17], v[12:13]
	v_pk_mul_f32 v[16:17], v[30:31], v[32:33] op_sel_hi:[1,0]
	s_nop 0
	v_pk_mul_f32 v[14:15], v[16:17], v[14:15]
	global_store_dwordx4 v[4:5], v[12:15], off offset:3072
	v_lshl_add_u64 v[4:5], v[4:5], 0, s[16:17]
	s_andn2_b64 exec, exec, s[8:9]
	s_cbranch_execnz .LBB0_13

; __device__ __forceinline__ void run_phase(const Params& P, char* shm, int ph, int bid, int nb) {
;   if (ph == 0) { phase_prep(P, shm, bid, nb); return; }
;   if (ph == N_PHASES - 1) { phase_final(P.x, P.final_g, bid, nb); return; }
;   int q = ph - 1;
;   int grp = q / PH_PER_GRP;
;   int qq = q % PH_PER_GRP;
;   float* xg = P.x + (long)P.gtok0 * D;
;   const int nM = P.tg / 256;
;   if (qq == 0) { phase_x0(P, P.gtok0, xg, P.xn, P.sq1, P.tg, bid, nb); return; }
;   int l = (qq - 1) / PH_PER_LAYER;
;   int s = (qq - 1) % PH_PER_LAYER;
;   switch (s) {
; template <bool COOP>
; __global__ void __launch_bounds__(NTHR) mega(KArgs K, int ph_lo, int ph_hi) {
;     ...
;       const int grp = (ph - 1) / PH_PER_GRP;
;       P.tg = grp <= 0 ? TG0 : TG1;
;       P.gtok0 = grp <= 0 ? 0 : TG0;
.LBB0_17:
	s_cmp_lt_i32 s42, 34
	s_mov_b32 s4, 0xc000
	s_cselect_b32 s93, s4, 0x8000
	s_cselect_b32 s75, 0, 0xc000
	s_add_i32 s4, s42, -1
	s_mul_hi_i32 s5, s4, 0x3e0f83e1
	s_lshr_b32 s6, s5, 31
	s_ashr_i32 s5, s5, 3
	s_add_i32 s5, s5, s6
	s_mul_i32 s5, s5, 33
	s_sub_i32 s27, s4, s5
	s_lshl_b32 s4, s75, 12
	s_mov_b32 s5, s59
	s_cmp_lg_u32 s27, 0
	v_writelane_b32 v249, s4, 56
	s_nop 1
	v_writelane_b32 v249, s5, 57
	s_cbranch_scc0 .LBB0_53
	s_add_i32 s4, s27, -1
	s_bfe_i32 s5, s4, 0x80000
	s_bfe_u32 s5, s5, 0x3000c
	s_add_i32 s5, s4, s5
	s_bfe_i32 s6, s5, 0x80000
	s_sext_i32_i16 s6, s6
	s_and_b32 s5, s5, 0xf8
	s_lshr_b32 s45, s6, 3
	s_ashr_i32 s6, s6, 3
	s_sub_i32 s4, s4, s5
	v_writelane_b32 v249, s6, 58
	s_and_b32 s28, s4, 0xff
	s_lshr_b32 s4, s93, 8
	v_writelane_b32 v249, s4, 59
	s_add_u32 s4, s2, 0x8400800
	s_addc_u32 s5, s3, 0
	s_add_u32 s54, s2, 0x30e00000
	s_addc_u32 s55, s3, 0
	s_add_u32 s12, s2, 0x3ce00000
	v_writelane_b32 v249, s4, 60
	s_addc_u32 s13, s3, 0
	v_writelane_b32 v248, s54, 0
	v_writelane_b32 v249, s5, 61
	s_add_u32 s4, s2, 0x4dc04040
	v_writelane_b32 v249, s4, 62
	s_addc_u32 s4, s3, 0
	v_writelane_b32 v249, s4, 63
	s_cmp_lt_i32 s28, 4
	s_mov_b64 s[4:5], -1
	v_writelane_b32 v248, s55, 1
	s_cbranch_scc1 .LBB0_150
	v_readlane_b32 s4, v250, 0
	v_readlane_b32 s6, v250, 2
	v_readlane_b32 s7, v250, 3
	v_readlane_b32 s6, v249, 56
	v_readlane_b32 s5, v250, 1
	v_readlane_b32 s7, v249, 57
	s_add_u32 s6, s4, s6
	s_addc_u32 s7, s5, 0
	s_add_u32 s29, s2, 0x4df14040
	s_addc_u32 s30, s3, 0
	s_and_b32 s31, 0xffff, s28
	s_cmp_lt_i32 s31, 6
	s_mov_b64 s[4:5], -1
	s_cbranch_scc1 .LBB0_85
	s_cmp_lt_i32 s31, 7
	s_cbranch_scc1 .LBB0_55
	s_cmp_eq_u32 s31, 7
	s_cbranch_scc0 .LBB0_54
	s_lshr_b32 s16, s93, 6
	v_readlane_b32 s4, v249, 1
	s_cmp_ge_i32 s4, s16
	s_cbranch_scc1 .LBB0_54
	v_readlane_b32 s4, v249, 58
	s_mul_i32 s4, s4, 0x2c0000
	s_ashr_i32 s5, s4, 31
	s_lshl_b64 s[4:5], s[4:5], 1
	v_readlane_b32 s8, v249, 52
	v_readlane_b32 s9, v249, 53
	s_add_u32 s17, s8, s4
	s_addc_u32 s18, s9, s5
	s_add_u32 s19, s2, s4
	s_addc_u32 s20, s3, s5
	s_mov_b64 s[8:9], 0
	v_readlane_b32 s21, v249, 1
	s_branch .LBB0_25
	s_nop 0
	s_nop 0
	s_nop 0
	s_nop 0
	s_nop 0
	s_nop 0
	s_nop 0
	s_nop 0
	s_nop 0
	s_nop 0
	s_nop 0
	s_nop 0
	s_nop 0
	s_nop 0
	s_nop 0
	s_nop 0
	s_nop 0
	s_nop 0
	s_nop 0
	s_nop 0
	s_nop 0
	s_nop 0
	s_nop 0
	s_nop 0
	s_nop 0
	s_nop 0
	s_nop 0
	s_nop 0
	s_nop 0
	s_nop 0
	s_nop 0
	s_nop 0
	s_nop 0
	s_nop 0
	s_nop 0
	s_nop 0
	s_nop 0
	s_nop 0
	s_nop 0
	s_nop 0
	s_nop 0
	s_nop 0
	s_nop 0
	s_nop 0
	s_nop 0
	s_nop 0
	s_nop 0
	s_nop 0
	s_nop 0
	s_nop 0
	s_nop 0

; __device__ __forceinline__ int tid_() { int t = threadIdx.x; asm volatile("" : "+v"(t)); return t; }
; __device__ __forceinline__ void phase_x0(const Params& P, int gtok0, float* x, u16* xb, float* sq, int nrows, int bid, int nb) {
;   const int tidn = tid_();
;   int wid = tidn >> 6, lane = tidn & 63;
;   for (int r = bid * 8 + wid; r < nrows; r += nb * 8) {
;     const int gr = gtok0 + r;
;     const float* xr = gr < S_PROMPT ? P.x_prompt + (long)gr * D : P.x_sample + (long)(gr - S_PROMPT) * D;
;     float ss = 0.f;
; #pragma unroll
;     for (int i = 0; i < 4; ++i) {
;       float4 v = *(const float4*)(xr + i * 256 + lane * 4);
;       ss += v.x * v.x + v.y * v.y + v.z * v.z + v.w * v.w;
;       *(float4*)(x + (long)r * D + i * 256 + lane * 4) = v;
;       u16x4 o;
;       o[0] = f2bf(v.x); o[1] = f2bf(v.y); o[2] = f2bf(v.z); o[3] = f2bf(v.w);
;       *(u16x4*)(xb + (long)r * D + i * 256 + lane * 4) = o;
;     }
; #pragma unroll
;     for (int o = 32; o >= 1; o >>= 1) ss += shfl_xor_l(ss, lane, o);
;     if (lane < 16) sq[(long)r * 16 + lane] = lane == 0 ? ss : 0.f;
;   }
.LBB0_411:
	v_add_u32_e32 v17, s75, v10
	v_readlane_b32 s12, v250, 12
	v_cmp_gt_i32_e64 s[6:7], s73, v17
	v_add_u32_e32 v17, 0xffffc000, v17
	v_readlane_b32 s13, v250, 13
	v_readlane_b32 s15, v250, 15
	s_waitcnt lgkmcnt(0)
	v_cndmask_b32_e64 v18, v17, v8, s[6:7]
	v_readlane_b32 s14, v250, 14
	v_mov_b32_e32 v17, s15
	v_mov_b32_e32 v20, s13
	v_cndmask_b32_e64 v19, 0, v9, s[6:7]
	v_cndmask_b32_e64 v21, v17, v20, s[6:7]
	v_mov_b32_e32 v17, s14
	v_mov_b32_e32 v20, s12
	v_cndmask_b32_e64 v20, v17, v20, s[6:7]
	v_lshlrev_b64 v[18:19], 12, v[18:19]
	v_lshl_add_u64 v[18:19], v[20:21], 0, v[18:19]
	v_lshl_add_u64 v[22:23], v[18:19], 0, v[0:1]
	global_load_dwordx4 v[18:21], v[22:23], off
	global_load_dwordx4 v[196:199], v[22:23], off offset:1024
	global_load_dwordx4 v[200:203], v[22:23], off offset:2048
	global_load_dwordx4 v[204:207], v[22:23], off offset:3072
	v_lshl_add_u64 v[24:25], s[2:3], 0, v[6:7]
	s_mov_b32 s6, 0x8400000
	v_add_co_u32_e64 v24, s[6:7], s6, v24
	v_readlane_b32 s16, v250, 16
	s_nop 0
	v_addc_co_u32_e64 v25, s[6:7], 0, v25, s[6:7]
	v_readlane_b32 s17, v250, 17
	v_readlane_b32 s18, v250, 18
	v_readlane_b32 s19, v250, 19
	v_readlane_b32 s20, v250, 20
	v_readlane_b32 s21, v250, 21
	v_readlane_b32 s22, v250, 22
	v_readlane_b32 s23, v250, 23
	v_readlane_b32 s24, v250, 24
	v_readlane_b32 s25, v250, 25
	v_readlane_b32 s26, v250, 26
	v_readlane_b32 s27, v250, 27
	s_waitcnt vmcnt(0)
	v_pk_mul_f32 v[28:29], v[20:21], v[20:21]
	global_store_dwordx4 v[4:5], v[18:21], off
	v_pk_mul_f32 v[26:27], v[18:19], v[18:19]
	s_nop 0
	v_cvt_pk_bf16_f32 v21, v20, v21
	v_cvt_pk_bf16_f32 v20, v18, v19
	global_store_dwordx2 v[24:25], v[20:21], off offset:2048
	s_nop 1
	v_mov_b64_e32 v[18:19], v[196:197]
	v_mov_b64_e32 v[20:21], v[198:199]
	v_add_f32_e32 v17, v26, v27
	v_add_f32_e32 v17, v17, v28
	v_add_f32_e32 v17, v17, v29
	s_nop 0
	v_pk_mul_f32 v[32:33], v[20:21], v[20:21]
	global_store_dwordx4 v[4:5], v[18:21], off offset:1024
	v_pk_mul_f32 v[30:31], v[18:19], v[18:19]
	s_nop 0
	v_cvt_pk_bf16_f32 v21, v20, v21
	v_cvt_pk_bf16_f32 v20, v18, v19
	global_store_dwordx2 v[24:25], v[20:21], off offset:2560
	s_nop 1
	v_mov_b64_e32 v[18:19], v[200:201]
	v_mov_b64_e32 v[20:21], v[202:203]
	v_add_f32_e32 v26, v30, v31
	v_add_f32_e32 v26, v26, v32
	v_add_f32_e32 v26, v26, v33
	v_add_f32_e32 v17, v17, v26
	s_nop 0
	v_pk_mul_f32 v[36:37], v[20:21], v[20:21]
	global_store_dwordx4 v[4:5], v[18:21], off offset:2048
	v_pk_mul_f32 v[34:35], v[18:19], v[18:19]
	s_nop 0
	v_cvt_pk_bf16_f32 v21, v20, v21
	v_cvt_pk_bf16_f32 v20, v18, v19
	global_store_dwordx2 v[24:25], v[20:21], off offset:3072
	s_nop 1
	v_mov_b64_e32 v[18:19], v[204:205]
	v_mov_b64_e32 v[20:21], v[206:207]
	v_add_f32_e32 v26, v34, v35
	v_add_f32_e32 v26, v26, v36
	v_add_f32_e32 v26, v26, v37
	v_add_f32_e32 v17, v17, v26
	s_nop 0
	v_pk_mul_f32 v[22:23], v[18:19], v[18:19]
	v_pk_mul_f32 v[38:39], v[20:21], v[20:21]
	v_add_f32_e32 v22, v22, v23
	v_add_f32_e32 v22, v22, v38
	v_add_f32_e32 v22, v22, v39
	v_add_f32_e32 v17, v17, v22
	global_store_dwordx4 v[4:5], v[18:21], off offset:3072
	s_nop 1
	v_cvt_pk_bf16_f32 v21, v20, v21
	v_cvt_pk_bf16_f32 v20, v18, v19
	ds_bpermute_b32 v18, v11, v17
	global_store_dwordx2 v[24:25], v[20:21], off offset:3584
	s_waitcnt lgkmcnt(0)
	v_add_f32_e32 v17, v17, v18
	ds_bpermute_b32 v18, v12, v17
	s_waitcnt lgkmcnt(0)
	v_add_f32_e32 v17, v17, v18
	ds_bpermute_b32 v18, v13, v17
	s_waitcnt lgkmcnt(0)
	v_add_f32_e32 v17, v17, v18
	ds_bpermute_b32 v18, v14, v17
	s_waitcnt lgkmcnt(0)
	v_add_f32_e32 v17, v17, v18
	ds_bpermute_b32 v18, v15, v17
	s_waitcnt lgkmcnt(0)
	v_add_f32_e32 v17, v17, v18
	ds_bpermute_b32 v18, v16, v17
	s_and_saveexec_b64 s[6:7], vcc
	s_cbranch_execz .LBB0_410
	s_waitcnt lgkmcnt(0)
	v_add_f32_e32 v17, v17, v18
	v_lshl_add_u64 v[20:21], s[2:3], 0, v[2:3]
	v_cndmask_b32_e64 v17, 0, v17, s[4:5]
	global_store_dword v[20:21], v17, off
	s_branch .LBB0_410
